# v99 + sc1 policy on the P0 prologue stores (XN bf16/fp8 rows and converted weight tiles): lines are written through and not kept in the writer XCD's L2
# speedup vs baseline: 1.0025x; 1.0025x over previous
; __device__ __forceinline__ void p0_fold_item(const float* w_in, const float* w_pool, const float* pscale, int k0, int n0z, bf16_t* WT, int drow0, int lane) {
;     const int n = lane & 31, kh = lane >> 5, g = n0z >> 7, d = (n0z & 127) + n;
;     float acc[4] = {0.f, 0.f, 0.f, 0.f};
;     const float* wrow = w_in + (size_t)(k0 + 4 * kh) * NIN + 3 * NA + 128 * g;
;     const float* wp = w_pool + (size_t)g * 128 * 128 + d;
; #pragma unroll 8
;     for (int c4 = 0; c4 < 32; ++c4) {
;         const float p0 = wp[(4 * c4 + 0) * 128], p1 = wp[(4 * c4 + 1) * 128], p2 = wp[(4 * c4 + 2) * 128], p3 = wp[(4 * c4 + 3) * 128];
; #pragma unroll
;         for (int i = 0; i < 4; ++i) { const f32x4 w = *(const f32x4*)(wrow + (size_t)i * NIN + 4 * c4); acc[i] += (w[0] * p0 + w[1] * p1) + (w[2] * p2 + w[3] * p3); }
;     }
.LBB0_17:
	v_lshl_add_u64 v[22:23], v[38:39], 0, s[82:83]
	s_mov_b64 s[0:1], 0x1800
	s_waitcnt lgkmcnt(2)
	v_lshl_add_u64 v[8:9], v[22:23], 0, s[0:1]
	s_mov_b64 s[0:1], 0x3800
	v_lshl_add_u64 v[10:11], v[22:23], 0, s[0:1]
	v_lshl_add_u64 v[12:13], v[22:23], 0, s[68:69]
	v_add_co_u32_e32 v2, vcc, 0xffffd000, v36
	global_load_dword v45, v[36:37], off offset:-4096
	global_load_dword v46, v[36:37], off offset:-3584
	global_load_dword v47, v[36:37], off offset:-3072
	global_load_dword v48, v[36:37], off offset:-2560
	global_load_dword v49, v[36:37], off offset:-2048
	global_load_dword v50, v[36:37], off offset:-1536
	global_load_dword v51, v[36:37], off offset:-1024
	global_load_dword v52, v[36:37], off offset:-512
	global_load_dword v53, v[36:37], off
	v_lshl_add_u64 v[14:15], v[22:23], 0, s[70:71]
	global_load_dwordx4 v[16:19], v[12:13], off offset:16
	global_load_dwordx4 v[28:31], v[8:9], off offset:16
	global_load_dwordx4 v[72:75], v[14:15], off offset:16
	global_load_dwordx4 v[76:79], v[10:11], off offset:16
	global_load_dwordx4 v[80:83], v[12:13], off offset:32
	global_load_dwordx4 v[84:87], v[8:9], off offset:32
	global_load_dwordx4 v[88:91], v[14:15], off offset:32
	global_load_dwordx4 v[92:95], v[10:11], off offset:32
	global_load_dwordx4 v[106:109], v[12:13], off offset:48
	global_load_dwordx4 v[120:123], v[8:9], off offset:48
	global_load_dwordx4 v[124:127], v[10:11], off offset:48
	global_load_dwordx4 v[128:131], v[14:15], off offset:48
	s_mov_b64 s[4:5], vcc
	s_waitcnt lgkmcnt(0)
	v_add_co_u32_e64 v6, s[8:9], s92, v36
	v_add_co_u32_e64 v4, s[6:7], s93, v36
	v_add_co_u32_e32 v20, vcc, 0x1000, v22
	s_mov_b64 s[10:11], vcc
	v_addc_co_u32_e64 v7, vcc, -1, v37, s[8:9]
	v_addc_co_u32_e64 v5, vcc, -1, v37, s[6:7]
	v_addc_co_u32_e64 v3, vcc, -1, v37, s[4:5]
	v_lshl_add_u64 v[24:25], v[22:23], 0, s[72:73]
	v_lshl_add_u64 v[26:27], v[22:23], 0, s[74:75]
	v_lshl_add_u64 v[32:33], v[22:23], 0, s[76:77]
	v_lshl_add_u64 v[58:59], v[22:23], 0, s[78:79]
	v_add_co_u32_e32 v14, vcc, 0x3000, v22
	global_load_dword v62, v[6:7], off offset:-3584
	global_load_dword v63, v[6:7], off offset:-3072
	global_load_dwordx4 v[132:135], v[32:33], off offset:16
	global_load_dwordx4 v[136:139], v[24:25], off offset:16
	global_load_dword v68, v[6:7], off offset:-2560
	global_load_dword v69, v[6:7], off offset:-2048
	global_load_dword v66, v[6:7], off offset:-1536
	global_load_dword v67, v[6:7], off offset:-1024
	global_load_dwordx4 v[140:143], v[58:59], off offset:16
	global_load_dwordx4 v[148:151], v[26:27], off offset:16
	global_load_dword v70, v[6:7], off offset:-512
	global_load_dword v71, v[6:7], off
	global_load_dword v54, v[4:5], off offset:-3584
	global_load_dword v55, v[4:5], off offset:-3072
	global_load_dwordx4 v[152:155], v[32:33], off offset:32
	global_load_dwordx4 v[156:159], v[24:25], off offset:32
	global_load_dword v56, v[4:5], off offset:-2560
	global_load_dword v57, v[4:5], off offset:-2048
	global_load_dwordx4 v[164:167], v[24:25], off offset:48
	global_load_dwordx4 v[10:13], v[26:27], off offset:48
	global_load_dwordx4 v[168:171], v[58:59], off offset:32
	global_load_dwordx4 v[172:175], v[26:27], off offset:32
	global_load_dwordx4 v[176:179], v[32:33], off offset:48
	global_load_dwordx4 v[180:183], v[58:59], off offset:48
	global_load_dword v64, v[4:5], off offset:-1536
	global_load_dword v65, v[4:5], off offset:-1024
	global_load_dword v44, v[4:5], off offset:-512
	s_mov_b64 s[6:7], vcc
	global_load_dword v58, v[2:3], off offset:-3584
	global_load_dword v59, v[2:3], off offset:-3072
	global_load_dword v60, v[2:3], off offset:-2560
	global_load_dword v61, v[2:3], off offset:-2048
	v_addc_co_u32_e64 v21, vcc, 0, v23, s[10:11]
	global_load_dword v32, v[2:3], off offset:-1536
	global_load_dword v33, v[2:3], off offset:-1024
	global_load_dword v26, v[2:3], off offset:-512
	global_load_dword v27, v[2:3], off
	global_load_dwordx4 v[6:9], v[20:21], off offset:2048
	v_add_co_u32_e32 v24, vcc, 0x5000, v22
	s_mov_b64 s[4:5], vcc
	v_addc_co_u32_e64 v15, vcc, 0, v23, s[6:7]
	global_load_dwordx4 v[2:5], v[20:21], off offset:2112
	v_addc_co_u32_e64 v25, s[4:5], 0, v23, s[4:5]
	s_add_u32 s82, s82, 0x80
	s_addc_u32 s83, s83, 0
	v_lshl_add_u64 v[36:37], v[36:37], 0, s[80:81]
	s_cmpk_eq_i32 s82, 0x200
	s_waitcnt vmcnt(46)
	v_mov_b32_e32 v186, v74
	s_waitcnt vmcnt(45)
	v_pk_mov_b32 v[184:185], v[72:73], v[76:77] op_sel:[1,0]
	v_pk_mov_b32 v[188:189], v[74:75], v[78:79] op_sel:[1,0]
	s_waitcnt vmcnt(44)
	v_mov_b32_e32 v102, v80
	s_waitcnt vmcnt(43)
	v_pk_mov_b32 v[112:113], v[80:81], v[84:85] op_sel:[1,0]
	v_mov_b32_e32 v98, v82
	v_pk_mov_b32 v[114:115], v[82:83], v[86:87] op_sel:[1,0]
	s_waitcnt vmcnt(41)
	v_mov_b32_e32 v97, v93
	v_pk_mov_b32 v[116:117], v[88:89], v[92:93] op_sel:[1,0]
	v_mov_b32_e32 v101, v95
	v_pk_mov_b32 v[118:119], v[90:91], v[94:95] op_sel:[1,0]
	s_waitcnt vmcnt(40)
	v_mov_b32_e32 v104, v106
	s_waitcnt vmcnt(39)
	v_mov_b32_e32 v105, v121
	v_pk_mov_b32 v[120:121], v[106:107], v[120:121] op_sel:[1,0]
	v_mov_b32_e32 v106, v108
	v_mov_b32_e32 v107, v123
	v_pk_mov_b32 v[122:123], v[108:109], v[122:123] op_sel:[1,0]
	s_waitcnt vmcnt(37)
	v_mov_b32_e32 v108, v128
	v_mov_b32_e32 v109, v125
	v_pk_mov_b32 v[124:125], v[128:129], v[124:125] op_sel:[1,0]
	v_mov_b32_e32 v110, v130
	v_mov_b32_e32 v111, v127
	v_pk_mov_b32 v[126:127], v[130:131], v[126:127] op_sel:[1,0]
	s_waitcnt vmcnt(33)
	v_mov_b32_e32 v73, v137
	v_pk_mov_b32 v[128:129], v[132:133], v[136:137] op_sel:[1,0]
	v_mov_b32_e32 v75, v139
	v_pk_mov_b32 v[130:131], v[134:135], v[138:139] op_sel:[1,0]
	s_waitcnt vmcnt(22)
	v_mov_b32_e32 v80, v152
	s_waitcnt vmcnt(21)
; __device__ __forceinline__ void p0_fold_item(const float* w_in, const float* w_pool, const float* pscale, int k0, int n0z, bf16_t* WT, int drow0, int lane) {
;     ...
;     for (int c4 = 0; c4 < 32; ++c4) {
;         const float p0 = wp[(4 * c4 + 0) * 128], p1 = wp[(4 * c4 + 1) * 128], p2 = wp[(4 * c4 + 2) * 128], p3 = wp[(4 * c4 + 3) * 128];
; #pragma unroll
;         for (int i = 0; i < 4; ++i) { const f32x4 w = *(const f32x4*)(wrow + (size_t)i * NIN + 4 * c4); acc[i] += (w[0] * p0 + w[1] * p1) + (w[2] * p2 + w[3] * p3); }
;     }
	v_pk_mov_b32 v[136:137], v[152:153], v[156:157] op_sel:[1,0]
	v_mov_b32_e32 v82, v154
	v_pk_mov_b32 v[138:139], v[154:155], v[158:159] op_sel:[1,0]
	s_waitcnt vmcnt(13)
	v_pk_mov_b32 v[152:153], v[180:181], v[10:11] op_sel:[1,0]
	v_pk_mov_b32 v[154:155], v[182:183], v[12:13] op_sel:[1,0]
	v_mov_b32_e32 v93, v11
	v_mov_b32_e32 v95, v13
	global_load_dwordx4 v[10:13], v[14:15], off offset:2048
	v_mov_b32_e32 v20, v16
	v_pk_mov_b32 v[16:17], v[16:17], v[28:29] op_sel:[1,0]
	v_mov_b32_e32 v21, v29
	s_waitcnt vmcnt(5)
	v_pk_mul_f32 v[16:17], v[32:33], v[16:17] op_sel:[1,0] op_sel_hi:[0,1]
	v_mov_b32_e32 v28, v18
	v_mov_b32_e32 v29, v31
	v_pk_mov_b32 v[30:31], v[18:19], v[30:31] op_sel:[1,0]
	v_mov_b32_e32 v18, v72
	v_mov_b32_e32 v19, v77
	v_mov_b32_e32 v81, v157
	v_pk_fma_f32 v[156:157], v[32:33], v[20:21], v[16:17]
	v_pk_mul_f32 v[20:21], v[32:33], v[184:185] op_sel:[1,0] op_sel_hi:[0,1]
	v_mov_b32_e32 v72, v132
	v_mov_b32_e32 v77, v149
	v_pk_mov_b32 v[132:133], v[140:141], v[148:149] op_sel:[1,0]
	v_mov_b32_e32 v83, v159
	v_pk_mov_b32 v[148:149], v[176:177], v[164:165] op_sel:[1,0]
	v_add_co_u32_e32 v164, vcc, 0x7000, v22
	global_load_dwordx4 v[14:17], v[14:15], off offset:2112
	v_pk_fma_f32 v[158:159], v[32:33], v[18:19], v[20:21]
	global_load_dwordx4 v[18:21], v[24:25], off offset:2048
	v_mov_b32_e32 v187, v79
	v_mov_b32_e32 v89, v165
	v_addc_co_u32_e32 v165, vcc, 0, v23, vcc
	s_waitcnt vmcnt(5)
	v_pk_mul_f32 v[30:31], v[26:27], v[30:31] op_sel:[1,0] op_sel_hi:[0,1]
	v_pk_mul_f32 v[32:33], v[26:27], v[188:189] op_sel:[1,0] op_sel_hi:[0,1]
	v_mov_b32_e32 v74, v134
	v_mov_b32_e32 v76, v140
	v_mov_b32_e32 v79, v151
	v_pk_mov_b32 v[134:135], v[142:143], v[150:151] op_sel:[1,0]
	v_mov_b32_e32 v84, v168
	v_pk_mov_b32 v[140:141], v[168:169], v[172:173] op_sel:[1,0]
	v_mov_b32_e32 v91, v167
	v_pk_mov_b32 v[150:151], v[178:179], v[166:167] op_sel:[1,0]
	global_load_dwordx4 v[22:25], v[24:25], off offset:2112
	v_pk_fma_f32 v[166:167], v[26:27], v[28:29], v[30:31]
	v_pk_fma_f32 v[168:169], v[26:27], v[186:187], v[32:33]
	global_load_dwordx4 v[30:33], v[164:165], off offset:2048
	global_load_dwordx4 v[26:29], v[164:165], off offset:2112
	v_mov_b32_e32 v103, v85
	v_mov_b32_e32 v99, v87
	v_mov_b32_e32 v78, v142
	v_pk_mov_b32 v[142:143], v[170:171], v[174:175] op_sel:[1,0]
	v_pk_mul_f32 v[112:113], v[62:63], v[112:113] op_sel:[1,0] op_sel_hi:[0,1]
	v_pk_mul_f32 v[114:115], v[68:69], v[114:115] op_sel:[1,0] op_sel_hi:[0,1]
	v_mov_b32_e32 v85, v173
	v_mov_b32_e32 v86, v170
	v_mov_b32_e32 v87, v175
	v_pk_mul_f32 v[128:129], v[64:65], v[128:129] op_sel:[1,0] op_sel_hi:[0,1]
	v_pk_mul_f32 v[130:131], v[44:45], v[130:131] op_sel:[1,0] op_sel_hi:[0,1]
	v_pk_mul_f32 v[132:133], v[64:65], v[132:133] op_sel:[1,0] op_sel_hi:[0,1]
	v_pk_mul_f32 v[134:135], v[44:45], v[134:135] op_sel:[1,0] op_sel_hi:[0,1]
	v_pk_mul_f32 v[136:137], v[46:47], v[136:137] op_sel:[1,0] op_sel_hi:[0,1]
	v_pk_mul_f32 v[138:139], v[48:49], v[138:139] op_sel:[1,0] op_sel_hi:[0,1]
	v_pk_mul_f32 v[140:141], v[46:47], v[140:141] op_sel:[1,0] op_sel_hi:[0,1]
	v_pk_mul_f32 v[142:143], v[48:49], v[142:143] op_sel:[1,0] op_sel_hi:[0,1]
	v_pk_fma_f32 v[102:103], v[62:63], v[102:103], v[112:113]
	s_waitcnt vmcnt(7)
	v_mov_b32_e32 v113, v7
	v_pk_fma_f32 v[98:99], v[68:69], v[98:99], v[114:115]
	v_mov_b32_e32 v115, v9
	v_pk_fma_f32 v[72:73], v[64:65], v[72:73], v[128:129]
	v_pk_fma_f32 v[74:75], v[44:45], v[74:75], v[130:131]
	v_pk_fma_f32 v[64:65], v[64:65], v[76:77], v[132:133]
	v_pk_fma_f32 v[44:45], v[44:45], v[78:79], v[134:135]
	v_pk_fma_f32 v[76:77], v[46:47], v[80:81], v[136:137]
	v_pk_fma_f32 v[78:79], v[48:49], v[82:83], v[138:139]
	v_pk_fma_f32 v[46:47], v[46:47], v[84:85], v[140:141]
	v_pk_fma_f32 v[48:49], v[48:49], v[86:87], v[142:143]
	v_mov_b32_e32 v96, v88
	v_mov_b32_e32 v100, v90
	v_pk_mul_f32 v[116:117], v[62:63], v[116:117] op_sel:[1,0] op_sel_hi:[0,1]
	v_pk_mul_f32 v[118:119], v[68:69], v[118:119] op_sel:[1,0] op_sel_hi:[0,1]
	v_pk_mul_f32 v[120:121], v[66:67], v[120:121] op_sel:[1,0] op_sel_hi:[0,1]
	v_pk_mul_f32 v[122:123], v[70:71], v[122:123] op_sel:[1,0] op_sel_hi:[0,1]
	v_pk_mul_f32 v[124:125], v[66:67], v[124:125] op_sel:[1,0] op_sel_hi:[0,1]
	v_pk_mul_f32 v[126:127], v[70:71], v[126:127] op_sel:[1,0] op_sel_hi:[0,1]
	v_mov_b32_e32 v88, v176
	v_mov_b32_e32 v90, v178
	s_waitcnt vmcnt(5)
	v_mov_b32_e32 v85, v11
	v_mov_b32_e32 v87, v13
	v_mov_b32_e32 v94, v182
	v_pk_mul_f32 v[148:149], v[50:51], v[148:149] op_sel:[1,0] op_sel_hi:[0,1]
	v_pk_mul_f32 v[150:151], v[52:53], v[150:151] op_sel:[1,0] op_sel_hi:[0,1]
	v_pk_mul_f32 v[154:155], v[52:53], v[154:155] op_sel:[1,0] op_sel_hi:[0,1]
	v_pk_fma_f32 v[62:63], v[62:63], v[96:97], v[116:117]
	v_pk_fma_f32 v[68:69], v[68:69], v[100:101], v[118:119]
	v_pk_fma_f32 v[96:97], v[66:67], v[104:105], v[120:121]
	v_pk_fma_f32 v[100:101], v[70:71], v[106:107], v[122:123]
	v_pk_fma_f32 v[66:67], v[66:67], v[108:109], v[124:125]
	v_pk_fma_f32 v[70:71], v[70:71], v[110:111], v[126:127]
	v_mov_b32_e32 v105, v3
	v_mov_b32_e32 v107, v5
	v_mov_b32_e32 v92, v180
	v_pk_mul_f32 v[152:153], v[50:51], v[152:153] op_sel:[1,0] op_sel_hi:[0,1]
	v_pk_fma_f32 v[80:81], v[50:51], v[88:89], v[148:149]
	v_pk_fma_f32 v[82:83], v[52:53], v[90:91], v[150:151]
	v_pk_fma_f32 v[52:53], v[52:53], v[94:95], v[154:155]
	v_pk_add_f32 v[88:89], v[156:157], v[166:167]
	v_pk_add_f32 v[90:91], v[158:159], v[168:169]
	v_pk_add_f32 v[66:67], v[66:67], v[70:71]
	s_waitcnt vmcnt(3)
; #define GAS __attribute__((address_space(1)))
; __host__ __device__ __forceinline__ size_t tl_off(int row, int k, int K) { return ((((size_t)(row >> 4) * (size_t)(K >> 5)) + (size_t)(k >> 5)) << 9) + (size_t)((row & 15) * 32 + (k & 31)); }
; __device__ __forceinline__ unsigned pk2(float lo, float hi) { return f2bf(lo) | (f2bf(hi) << 16); }
; __device__ __forceinline__ void p0_fold_item(const float* w_in, const float* w_pool, const float* pscale, int k0, int n0z, bf16_t* WT, int drow0, int lane) {
;     ...
;     for (int c4 = 0; c4 < 32; ++c4) {
;         const float p0 = wp[(4 * c4 + 0) * 128], p1 = wp[(4 * c4 + 1) * 128], p2 = wp[(4 * c4 + 2) * 128], p3 = wp[(4 * c4 + 3) * 128];
; #pragma unroll
;         for (int i = 0; i < 4; ++i) { const f32x4 w = *(const f32x4*)(wrow + (size_t)i * NIN + 4 * c4); acc[i] += (w[0] * p0 + w[1] * p1) + (w[2] * p2 + w[3] * p3); }
;     }
;     const float ps = pscale[n0z + n];
;     float hi[4];
; #pragma unroll
;     for (int i = 0; i < 4; ++i) { acc[i] *= ps; hi[i] = __shfl(acc[i], (lane + 32) & 63); }
;     if (lane < 32) { u32x4 o; o.x = pk2(acc[0], acc[1]); o.y = pk2(acc[2], acc[3]); o.z = pk2(hi[0], hi[1]); o.w = pk2(hi[2], hi[3]);
;         *(GAS u32x4*)(WT + tl_off(drow0 + n, k0, D)) = o; }
	v_pk_mov_b32 v[6:7], v[18:19], v[6:7] op_sel:[1,0]
	v_pk_mov_b32 v[8:9], v[20:21], v[8:9] op_sel:[1,0]
	v_mov_b32_e32 v112, v18
	v_mov_b32_e32 v114, v20
	v_pk_mul_f32 v[6:7], v[58:59], v[6:7] op_sel:[1,0] op_sel_hi:[0,1]
	v_pk_mul_f32 v[8:9], v[60:61], v[8:9] op_sel:[1,0] op_sel_hi:[0,1]
	v_pk_fma_f32 v[6:7], v[58:59], v[112:113], v[6:7]
	v_pk_fma_f32 v[8:9], v[60:61], v[114:115], v[8:9]
	v_mov_b32_e32 v71, v15
	v_pk_add_f32 v[6:7], v[6:7], v[8:9]
	v_mov_b32_e32 v95, v17
	v_pk_add_f32 v[6:7], v[42:43], v[6:7]
	v_pk_fma_f32 v[50:51], v[50:51], v[92:93], v[152:153]
	v_pk_add_f32 v[92:93], v[102:103], v[98:99]
	v_pk_add_f32 v[62:63], v[62:63], v[68:69]
	s_waitcnt vmcnt(2)
	v_pk_mov_b32 v[2:3], v[22:23], v[2:3] op_sel:[1,0]
	v_pk_mov_b32 v[4:5], v[24:25], v[4:5] op_sel:[1,0]
	s_waitcnt vmcnt(1)
	v_pk_mov_b32 v[10:11], v[30:31], v[10:11] op_sel:[1,0]
	v_pk_mov_b32 v[12:13], v[32:33], v[12:13] op_sel:[1,0]
	v_mov_b32_e32 v84, v30
	v_mov_b32_e32 v86, v32
	v_pk_mul_f32 v[10:11], v[58:59], v[10:11] op_sel:[1,0] op_sel_hi:[0,1]
	v_pk_mul_f32 v[12:13], v[60:61], v[12:13] op_sel:[1,0] op_sel_hi:[0,1]
	v_pk_fma_f32 v[8:9], v[58:59], v[84:85], v[10:11]
	v_pk_fma_f32 v[10:11], v[60:61], v[86:87], v[12:13]
	v_mov_b32_e32 v104, v22
	v_pk_add_f32 v[8:9], v[8:9], v[10:11]
	v_mov_b32_e32 v106, v24
	v_pk_mul_f32 v[2:3], v[54:55], v[2:3] op_sel:[1,0] op_sel_hi:[0,1]
	v_pk_mul_f32 v[4:5], v[56:57], v[4:5] op_sel:[1,0] op_sel_hi:[0,1]
	s_waitcnt vmcnt(0)
	v_pk_mov_b32 v[14:15], v[26:27], v[14:15] op_sel:[1,0]
	v_pk_mov_b32 v[16:17], v[28:29], v[16:17] op_sel:[1,0]
	v_pk_add_f32 v[8:9], v[40:41], v[8:9]
	v_mov_b32_e32 v70, v26
	v_mov_b32_e32 v94, v28
	v_pk_fma_f32 v[2:3], v[54:55], v[104:105], v[2:3]
	v_pk_fma_f32 v[4:5], v[56:57], v[106:107], v[4:5]
	v_pk_mul_f32 v[14:15], v[54:55], v[14:15] op_sel:[1,0] op_sel_hi:[0,1]
	v_pk_mul_f32 v[16:17], v[56:57], v[16:17] op_sel:[1,0] op_sel_hi:[0,1]
	v_pk_add_f32 v[6:7], v[6:7], v[88:89]
	v_pk_add_f32 v[8:9], v[8:9], v[90:91]
	v_pk_add_f32 v[68:69], v[96:97], v[100:101]
	v_pk_add_f32 v[2:3], v[2:3], v[4:5]
	v_pk_fma_f32 v[4:5], v[54:55], v[70:71], v[14:15]
	v_pk_fma_f32 v[12:13], v[56:57], v[94:95], v[16:17]
	v_pk_add_f32 v[6:7], v[6:7], v[92:93]
	v_pk_add_f32 v[8:9], v[8:9], v[62:63]
	v_pk_add_f32 v[4:5], v[4:5], v[12:13]
	v_pk_add_f32 v[6:7], v[6:7], v[68:69]
	v_pk_add_f32 v[8:9], v[8:9], v[66:67]
	v_pk_add_f32 v[72:73], v[72:73], v[74:75]
	v_pk_add_f32 v[44:45], v[64:65], v[44:45]
	v_pk_add_f32 v[2:3], v[6:7], v[2:3]
	v_pk_add_f32 v[4:5], v[8:9], v[4:5]
	v_pk_add_f32 v[64:65], v[76:77], v[78:79]
	v_pk_add_f32 v[46:47], v[46:47], v[48:49]
	v_pk_add_f32 v[2:3], v[2:3], v[72:73]
	v_pk_add_f32 v[4:5], v[4:5], v[44:45]
	v_pk_add_f32 v[48:49], v[80:81], v[82:83]
	v_pk_add_f32 v[50:51], v[50:51], v[52:53]
	v_pk_add_f32 v[2:3], v[2:3], v[64:65]
	v_pk_add_f32 v[4:5], v[4:5], v[46:47]
	v_pk_add_f32 v[42:43], v[2:3], v[48:49]
	v_pk_add_f32 v[40:41], v[4:5], v[50:51]
	s_cbranch_scc0 .LBB0_17
	s_lshl_b32 s0, s96, 5
	s_and_b32 s1, s0, 0x1e0
	v_or_b32_e32 v2, s1, v146
	v_lshlrev_b32_e32 v2, 2, v2
	global_load_dword v4, v2, s[50:51]
	s_waitcnt vmcnt(0)
	v_pk_mul_f32 v[2:3], v[42:43], v[4:5] op_sel_hi:[1,0]
	v_pk_mul_f32 v[4:5], v[40:41], v[4:5] op_sel_hi:[1,0]
	ds_bpermute_b32 v9, v160, v3
	ds_bpermute_b32 v8, v160, v5
	ds_bpermute_b32 v7, v160, v2
	ds_bpermute_b32 v6, v160, v4
	s_and_saveexec_b64 s[4:5], s[12:13]
	s_cbranch_execz .LBB0_15
	v_and_b32_sdwa v10, v3, v162 dst_sel:DWORD dst_unused:UNUSED_PAD src0_sel:WORD_1 src1_sel:DWORD
	v_and_b32_sdwa v11, v2, v162 dst_sel:DWORD dst_unused:UNUSED_PAD src0_sel:WORD_1 src1_sel:DWORD
	v_and_b32_sdwa v12, v5, v162 dst_sel:DWORD dst_unused:UNUSED_PAD src0_sel:WORD_1 src1_sel:DWORD
	v_and_b32_sdwa v13, v4, v162 dst_sel:DWORD dst_unused:UNUSED_PAD src0_sel:WORD_1 src1_sel:DWORD
	v_add3_u32 v11, v2, v11, s94
	v_add3_u32 v2, v3, v10, s94
	v_add3_u32 v3, v5, v12, s94
	v_add3_u32 v4, v4, v13, s94
	v_and_b32_e32 v3, 0xffff0000, v3
	v_and_b32_e32 v4, 0xffff0000, v4
	v_or_b32_sdwa v2, v3, v2 dst_sel:DWORD dst_unused:UNUSED_PAD src0_sel:DWORD src1_sel:WORD_1
	v_or_b32_sdwa v3, v4, v11 dst_sel:DWORD dst_unused:UNUSED_PAD src0_sel:DWORD src1_sel:WORD_1
	s_waitcnt lgkmcnt(3)
	v_bfe_u32 v4, v9, 16, 1
	v_add3_u32 v4, v9, v4, s94
	s_waitcnt lgkmcnt(2)
	v_bfe_u32 v5, v8, 16, 1
	s_lshr_b32 s6, s0, 1
	v_lshrrev_b32_e32 v4, 16, v4
	v_add3_u32 v5, v8, v5, s94
	s_lshl_b32 s1, s1, 2
	s_and_b32 s6, s6, 0x60
	s_and_b32 s0, s0, 0x100
	v_and_or_b32 v4, v5, s95, v4
	s_waitcnt lgkmcnt(1)
	v_bfe_u32 v5, v7, 16, 1
	s_and_b32 s1, s1, 0x80
	v_add3_u32 v5, v7, v5, s94
	s_waitcnt lgkmcnt(0)
	v_bfe_u32 v7, v6, 16, 1
	s_or_b32 s0, s0, s6
	v_lshrrev_b32_e32 v5, 16, v5
	v_add3_u32 v6, v6, v7, s94
	s_or_b32 s0, s0, s1
	v_and_or_b32 v5, v6, s95, v5
	v_or_b32_e32 v6, s0, v146
	s_ashr_i32 s0, s96, 6
	v_lshlrev_b32_e32 v6, 11, v6
	s_ashr_i32 s1, s0, 31
	v_and_b32_e32 v34, 0xf8000, v6
	v_and_or_b32 v8, s97, 24, v161
	v_lshl_add_u64 v[6:7], s[66:67], 0, v[34:35]
	s_lshl_b64 s[0:1], s[0:1], 10
	v_lshl_add_u64 v[6:7], v[6:7], 0, s[0:1]
	v_lshlrev_b32_e32 v34, 1, v8
	v_lshl_add_u64 v[6:7], v[6:7], 0, v[34:35]
	v_add_co_u32_e32 v6, vcc, 0x300000, v6
	s_nop 1
	v_addc_co_u32_e32 v7, vcc, 0, v7, vcc
	global_store_dwordx4 v[6:7], v[2:5], off sc1
	s_branch .LBB0_15

; #define LAS __attribute__((address_space(3)))
; __device__ __forceinline__ void p0_fold_staged(Frame& F) {
;     ...
;     {   const int nb = 8 * (F.vcu & 1) + wave, n0z = 32 * nb, g = nb >> 2, n = lane & 31, kh = lane >> 5, d = (n0z & 127) + n;
;         const LAS float* wp = Lp + (g - g0) * 128 * 128 + d;
;         const LAS float* wr = Lw + (4 * kh) * 512 + 128 * g;
;         float acc[4] = {0.f, 0.f, 0.f, 0.f};
; #pragma unroll 8
;         for (int c4 = 0; c4 < 32; ++c4) {
;             const float p0 = wp[(4 * c4 + 0) * 128], p1 = wp[(4 * c4 + 1) * 128], p2 = wp[(4 * c4 + 2) * 128], p3 = wp[(4 * c4 + 3) * 128];
; #pragma unroll
;             for (int i = 0; i < 4; ++i) { const f32x4 w = *(const LAS f32x4*)(wr + i * 512 + 4 * c4); acc[i] += (w[0] * p0 + w[1] * p1) + (w[2] * p2 + w[3] * p3); }
;         }
.LBB0_23:
	v_add_u32_e32 v8, 0, v6
	ds_read2st64_b32 v[136:137], v8 offset1:2
	ds_read2st64_b32 v[138:139], v8 offset0:4 offset1:6
	v_add_u32_e32 v9, 0, v7
	ds_read2st64_b32 v[140:141], v8 offset0:8 offset1:10
	ds_read2st64_b32 v[142:143], v8 offset0:12 offset1:14
	v_add_u32_e32 v10, 0x20000, v9
	v_add_u32_e32 v12, 0x20800, v9
	v_add_u32_e32 v16, 0x21000, v9
	v_add_u32_e32 v20, 0x21800, v9
	v_add_u32_e32 v24, 0x20010, v9
	v_add_u32_e32 v28, 0x20810, v9
	v_add_u32_e32 v32, 0x21010, v9
	v_add_u32_e32 v36, 0x21810, v9
	ds_read2st64_b32 v[146:147], v8 offset0:16 offset1:18
	ds_read2st64_b32 v[148:149], v8 offset0:20 offset1:22
	v_add_u32_e32 v40, 0x20020, v9
	v_add_u32_e32 v44, 0x20820, v9
	v_add_u32_e32 v48, 0x21020, v9
	v_add_u32_e32 v52, 0x21820, v9
	v_add_u32_e32 v56, 0x20030, v9
	v_add_u32_e32 v60, 0x20830, v9
	v_add_u32_e32 v64, 0x21030, v9
	v_add_u32_e32 v68, 0x21830, v9
	v_add_u32_e32 v72, 0x20040, v9
	v_add_u32_e32 v76, 0x20840, v9
	v_add_u32_e32 v80, 0x21040, v9
	v_add_u32_e32 v84, 0x21840, v9
	v_add_u32_e32 v88, 0x20050, v9
	v_add_u32_e32 v92, 0x20850, v9
	v_add_u32_e32 v96, 0x21050, v9
	v_add_u32_e32 v100, 0x21850, v9
	v_add_u32_e32 v104, 0x20060, v9
	v_add_u32_e32 v108, 0x20860, v9
	v_add_u32_e32 v112, 0x21060, v9
	v_add_u32_e32 v116, 0x21860, v9
	v_add_u32_e32 v120, 0x20070, v9
	v_add_u32_e32 v124, 0x20870, v9
	v_add_u32_e32 v128, 0x21070, v9
	v_add_u32_e32 v132, 0x21870, v9
	ds_read2st64_b32 v[150:151], v8 offset0:24 offset1:26
	ds_read2st64_b32 v[152:153], v8 offset0:28 offset1:30
	ds_read2st64_b32 v[154:155], v8 offset0:32 offset1:34
	ds_read2st64_b32 v[156:157], v8 offset0:36 offset1:38
	ds_read2st64_b32 v[158:159], v8 offset0:40 offset1:42
	ds_read2st64_b32 v[160:161], v8 offset0:44 offset1:46
	ds_read2st64_b32 v[162:163], v8 offset0:48 offset1:50
	ds_read2st64_b32 v[164:165], v8 offset0:52 offset1:54
	ds_read2st64_b32 v[166:167], v8 offset0:56 offset1:58
	ds_read2st64_b32 v[168:169], v8 offset0:60 offset1:62
	ds_read_b128 v[8:11], v10
	ds_read_b128 v[12:15], v12
	ds_read_b128 v[16:19], v16
	ds_read_b128 v[20:23], v20
	ds_read_b128 v[24:27], v24
	ds_read_b128 v[28:31], v28
	ds_read_b128 v[32:35], v32
	ds_read_b128 v[36:39], v36
	ds_read_b128 v[40:43], v40
	ds_read_b128 v[44:47], v44
	ds_read_b128 v[48:51], v48
	ds_read_b128 v[52:55], v52
	ds_read_b128 v[56:59], v56
	ds_read_b128 v[60:63], v60
	ds_read_b128 v[64:67], v64
	ds_read_b128 v[68:71], v68
	ds_read_b128 v[72:75], v72
	ds_read_b128 v[76:79], v76
	ds_read_b128 v[80:83], v80
	ds_read_b128 v[84:87], v84
	ds_read_b128 v[88:91], v88
	ds_read_b128 v[92:95], v92
	ds_read_b128 v[96:99], v96
	ds_read_b128 v[100:103], v100
	ds_read_b128 v[104:107], v104
	ds_read_b128 v[108:111], v108
	ds_read_b128 v[112:115], v112
	ds_read_b128 v[116:119], v116
	ds_read_b128 v[120:123], v120
	ds_read_b128 v[124:127], v124
	ds_read_b128 v[128:131], v128
	ds_read_b128 v[132:135], v132
	s_waitcnt lgkmcnt(14)
	v_mov_b32_e32 v171, v9
	v_pk_mov_b32 v[8:9], v[16:17], v[8:9] op_sel:[1,0]
	v_mov_b32_e32 v17, v11
	v_pk_mov_b32 v[10:11], v[18:19], v[10:11] op_sel:[1,0]
	v_mov_b32_e32 v19, v13
	v_pk_mov_b32 v[12:13], v[20:21], v[12:13] op_sel:[1,0]
	v_mov_b32_e32 v21, v15
	v_pk_mov_b32 v[14:15], v[22:23], v[14:15] op_sel:[1,0]
	v_mov_b32_e32 v170, v16
	v_mov_b32_e32 v16, v18
	v_mov_b32_e32 v18, v20
	v_mov_b32_e32 v20, v22
	v_mov_b32_e32 v23, v25
	v_pk_mov_b32 v[24:25], v[32:33], v[24:25] op_sel:[1,0]
	v_mov_b32_e32 v33, v27
	v_pk_mov_b32 v[26:27], v[34:35], v[26:27] op_sel:[1,0]
	v_mov_b32_e32 v35, v29
	v_pk_mov_b32 v[28:29], v[36:37], v[28:29] op_sel:[1,0]
	v_mov_b32_e32 v37, v31
	v_pk_mov_b32 v[30:31], v[38:39], v[30:31] op_sel:[1,0]
	v_pk_mul_f32 v[8:9], v[136:137], v[8:9] op_sel:[1,0] op_sel_hi:[0,1]
	v_pk_mul_f32 v[10:11], v[138:139], v[10:11] op_sel:[1,0] op_sel_hi:[0,1]
	v_pk_mul_f32 v[12:13], v[136:137], v[12:13] op_sel:[1,0] op_sel_hi:[0,1]
	v_pk_mul_f32 v[14:15], v[138:139], v[14:15] op_sel:[1,0] op_sel_hi:[0,1]
	v_mov_b32_e32 v22, v32
	v_mov_b32_e32 v32, v34
	v_mov_b32_e32 v34, v36
	v_mov_b32_e32 v36, v38
	v_mov_b32_e32 v39, v41
	v_pk_mov_b32 v[40:41], v[48:49], v[40:41] op_sel:[1,0]
	v_mov_b32_e32 v49, v43
	v_pk_mov_b32 v[42:43], v[50:51], v[42:43] op_sel:[1,0]
	v_mov_b32_e32 v51, v45
	v_pk_mov_b32 v[44:45], v[52:53], v[44:45] op_sel:[1,0]
	v_mov_b32_e32 v53, v47
	v_pk_mov_b32 v[46:47], v[54:55], v[46:47] op_sel:[1,0]
	v_pk_mul_f32 v[24:25], v[140:141], v[24:25] op_sel:[1,0] op_sel_hi:[0,1]
	v_pk_mul_f32 v[26:27], v[142:143], v[26:27] op_sel:[1,0] op_sel_hi:[0,1]
	v_pk_mul_f32 v[28:29], v[140:141], v[28:29] op_sel:[1,0] op_sel_hi:[0,1]
	v_pk_mul_f32 v[30:31], v[142:143], v[30:31] op_sel:[1,0] op_sel_hi:[0,1]
	v_pk_fma_f32 v[8:9], v[136:137], v[170:171], v[8:9]
	v_pk_fma_f32 v[10:11], v[138:139], v[16:17], v[10:11]
	v_pk_fma_f32 v[12:13], v[136:137], v[18:19], v[12:13]
	v_pk_fma_f32 v[14:15], v[138:139], v[20:21], v[14:15]
	v_mov_b32_e32 v38, v48
	v_mov_b32_e32 v48, v50
	v_mov_b32_e32 v50, v52
	v_mov_b32_e32 v52, v54
	v_mov_b32_e32 v55, v57
	v_pk_mov_b32 v[56:57], v[64:65], v[56:57] op_sel:[1,0]
	v_mov_b32_e32 v65, v59
	v_pk_mov_b32 v[58:59], v[66:67], v[58:59] op_sel:[1,0]
	v_mov_b32_e32 v67, v61
	v_pk_mov_b32 v[60:61], v[68:69], v[60:61] op_sel:[1,0]
	v_mov_b32_e32 v69, v63
	v_pk_mov_b32 v[62:63], v[70:71], v[62:63] op_sel:[1,0]
	v_pk_mul_f32 v[40:41], v[146:147], v[40:41] op_sel:[1,0] op_sel_hi:[0,1]
	v_pk_mul_f32 v[42:43], v[148:149], v[42:43] op_sel:[1,0] op_sel_hi:[0,1]
	v_pk_mul_f32 v[44:45], v[146:147], v[44:45] op_sel:[1,0] op_sel_hi:[0,1]
	v_pk_mul_f32 v[46:47], v[148:149], v[46:47] op_sel:[1,0] op_sel_hi:[0,1]
	v_pk_fma_f32 v[16:17], v[140:141], v[22:23], v[24:25]
	v_pk_fma_f32 v[18:19], v[142:143], v[32:33], v[26:27]
	v_pk_fma_f32 v[20:21], v[140:141], v[34:35], v[28:29]
	v_pk_fma_f32 v[22:23], v[142:143], v[36:37], v[30:31]
	v_pk_add_f32 v[8:9], v[8:9], v[10:11]
	v_pk_add_f32 v[10:11], v[12:13], v[14:15]
	v_mov_b32_e32 v54, v64
	v_mov_b32_e32 v64, v66
	v_mov_b32_e32 v66, v68
	v_mov_b32_e32 v68, v70
	v_mov_b32_e32 v71, v73
	s_waitcnt lgkmcnt(13)
; #define LAS __attribute__((address_space(3)))
; __device__ __forceinline__ void p0_fold_staged(Frame& F) {
;     ...
;         for (int c4 = 0; c4 < 32; ++c4) {
;             const float p0 = wp[(4 * c4 + 0) * 128], p1 = wp[(4 * c4 + 1) * 128], p2 = wp[(4 * c4 + 2) * 128], p3 = wp[(4 * c4 + 3) * 128];
; #pragma unroll
;             for (int i = 0; i < 4; ++i) { const f32x4 w = *(const LAS f32x4*)(wr + i * 512 + 4 * c4); acc[i] += (w[0] * p0 + w[1] * p1) + (w[2] * p2 + w[3] * p3); }
;         }
	v_pk_mov_b32 v[72:73], v[80:81], v[72:73] op_sel:[1,0]
	v_mov_b32_e32 v81, v75
	v_pk_mov_b32 v[74:75], v[82:83], v[74:75] op_sel:[1,0]
	v_mov_b32_e32 v83, v77
	s_waitcnt lgkmcnt(12)
	v_pk_mov_b32 v[76:77], v[84:85], v[76:77] op_sel:[1,0]
	v_mov_b32_e32 v85, v79
	v_pk_mov_b32 v[78:79], v[86:87], v[78:79] op_sel:[1,0]
	v_pk_mul_f32 v[56:57], v[150:151], v[56:57] op_sel:[1,0] op_sel_hi:[0,1]
	v_pk_mul_f32 v[58:59], v[152:153], v[58:59] op_sel:[1,0] op_sel_hi:[0,1]
	v_pk_mul_f32 v[60:61], v[150:151], v[60:61] op_sel:[1,0] op_sel_hi:[0,1]
	v_pk_mul_f32 v[62:63], v[152:153], v[62:63] op_sel:[1,0] op_sel_hi:[0,1]
	v_pk_fma_f32 v[24:25], v[146:147], v[38:39], v[40:41]
	v_pk_fma_f32 v[26:27], v[148:149], v[48:49], v[42:43]
	v_pk_fma_f32 v[28:29], v[146:147], v[50:51], v[44:45]
	v_pk_fma_f32 v[30:31], v[148:149], v[52:53], v[46:47]
	v_pk_add_f32 v[12:13], v[16:17], v[18:19]
	v_pk_add_f32 v[14:15], v[20:21], v[22:23]
	v_pk_add_f32 v[2:3], v[2:3], v[8:9]
	v_pk_add_f32 v[4:5], v[4:5], v[10:11]
	v_mov_b32_e32 v70, v80
	v_mov_b32_e32 v80, v82
	v_mov_b32_e32 v82, v84
	v_mov_b32_e32 v84, v86
	s_waitcnt lgkmcnt(11)
	v_mov_b32_e32 v87, v89
	s_waitcnt lgkmcnt(9)
	v_pk_mov_b32 v[88:89], v[96:97], v[88:89] op_sel:[1,0]
	v_mov_b32_e32 v97, v91
	v_pk_mov_b32 v[90:91], v[98:99], v[90:91] op_sel:[1,0]
	v_mov_b32_e32 v99, v93
	s_waitcnt lgkmcnt(8)
	v_pk_mov_b32 v[92:93], v[100:101], v[92:93] op_sel:[1,0]
	v_mov_b32_e32 v101, v95
	v_pk_mov_b32 v[94:95], v[102:103], v[94:95] op_sel:[1,0]
	v_pk_mul_f32 v[72:73], v[154:155], v[72:73] op_sel:[1,0] op_sel_hi:[0,1]
	v_pk_mul_f32 v[74:75], v[156:157], v[74:75] op_sel:[1,0] op_sel_hi:[0,1]
	v_pk_mul_f32 v[76:77], v[154:155], v[76:77] op_sel:[1,0] op_sel_hi:[0,1]
	v_pk_mul_f32 v[78:79], v[156:157], v[78:79] op_sel:[1,0] op_sel_hi:[0,1]
	v_pk_fma_f32 v[32:33], v[150:151], v[54:55], v[56:57]
	v_pk_fma_f32 v[34:35], v[152:153], v[64:65], v[58:59]
	v_pk_fma_f32 v[36:37], v[150:151], v[66:67], v[60:61]
	v_pk_fma_f32 v[38:39], v[152:153], v[68:69], v[62:63]
	v_pk_add_f32 v[16:17], v[24:25], v[26:27]
	v_pk_add_f32 v[18:19], v[28:29], v[30:31]
	v_pk_add_f32 v[2:3], v[2:3], v[12:13]
	v_pk_add_f32 v[4:5], v[4:5], v[14:15]
	v_mov_b32_e32 v86, v96
	v_mov_b32_e32 v96, v98
	v_mov_b32_e32 v98, v100
	v_mov_b32_e32 v100, v102
	s_waitcnt lgkmcnt(7)
	v_mov_b32_e32 v103, v105
	s_waitcnt lgkmcnt(5)
	v_pk_mov_b32 v[104:105], v[112:113], v[104:105] op_sel:[1,0]
	v_mov_b32_e32 v113, v107
	v_pk_mov_b32 v[106:107], v[114:115], v[106:107] op_sel:[1,0]
	v_mov_b32_e32 v115, v109
	s_waitcnt lgkmcnt(4)
	v_pk_mov_b32 v[108:109], v[116:117], v[108:109] op_sel:[1,0]
	v_mov_b32_e32 v117, v111
	v_pk_mov_b32 v[110:111], v[118:119], v[110:111] op_sel:[1,0]
	v_pk_mul_f32 v[88:89], v[158:159], v[88:89] op_sel:[1,0] op_sel_hi:[0,1]
	v_pk_mul_f32 v[90:91], v[160:161], v[90:91] op_sel:[1,0] op_sel_hi:[0,1]
	v_pk_mul_f32 v[92:93], v[158:159], v[92:93] op_sel:[1,0] op_sel_hi:[0,1]
	v_pk_mul_f32 v[94:95], v[160:161], v[94:95] op_sel:[1,0] op_sel_hi:[0,1]
	v_pk_fma_f32 v[40:41], v[154:155], v[70:71], v[72:73]
	v_pk_fma_f32 v[42:43], v[156:157], v[80:81], v[74:75]
	v_pk_fma_f32 v[44:45], v[154:155], v[82:83], v[76:77]
	v_pk_fma_f32 v[46:47], v[156:157], v[84:85], v[78:79]
	v_pk_add_f32 v[20:21], v[32:33], v[34:35]
	v_pk_add_f32 v[22:23], v[36:37], v[38:39]
	v_pk_add_f32 v[2:3], v[2:3], v[16:17]
	v_pk_add_f32 v[4:5], v[4:5], v[18:19]
	v_mov_b32_e32 v102, v112
	v_mov_b32_e32 v112, v114
	v_mov_b32_e32 v114, v116
	v_mov_b32_e32 v116, v118
	s_waitcnt lgkmcnt(3)
	v_mov_b32_e32 v119, v121
	s_waitcnt lgkmcnt(1)
	v_pk_mov_b32 v[120:121], v[128:129], v[120:121] op_sel:[1,0]
	v_mov_b32_e32 v129, v123
	v_pk_mov_b32 v[122:123], v[130:131], v[122:123] op_sel:[1,0]
	v_mov_b32_e32 v131, v125
	s_waitcnt lgkmcnt(0)
	v_pk_mov_b32 v[124:125], v[132:133], v[124:125] op_sel:[1,0]
	v_mov_b32_e32 v133, v127
	v_pk_mov_b32 v[126:127], v[134:135], v[126:127] op_sel:[1,0]
	v_pk_mul_f32 v[104:105], v[162:163], v[104:105] op_sel:[1,0] op_sel_hi:[0,1]
	v_pk_mul_f32 v[106:107], v[164:165], v[106:107] op_sel:[1,0] op_sel_hi:[0,1]
	v_pk_mul_f32 v[108:109], v[162:163], v[108:109] op_sel:[1,0] op_sel_hi:[0,1]
	v_pk_mul_f32 v[110:111], v[164:165], v[110:111] op_sel:[1,0] op_sel_hi:[0,1]
	v_pk_fma_f32 v[48:49], v[158:159], v[86:87], v[88:89]
	v_pk_fma_f32 v[50:51], v[160:161], v[96:97], v[90:91]
	v_pk_fma_f32 v[52:53], v[158:159], v[98:99], v[92:93]
	v_pk_fma_f32 v[54:55], v[160:161], v[100:101], v[94:95]
	v_pk_add_f32 v[24:25], v[40:41], v[42:43]
	v_pk_add_f32 v[26:27], v[44:45], v[46:47]
	v_pk_add_f32 v[2:3], v[2:3], v[20:21]
	v_pk_add_f32 v[4:5], v[4:5], v[22:23]
	v_mov_b32_e32 v118, v128
	v_mov_b32_e32 v128, v130
	v_mov_b32_e32 v130, v132
	v_mov_b32_e32 v132, v134
	v_pk_mul_f32 v[120:121], v[166:167], v[120:121] op_sel:[1,0] op_sel_hi:[0,1]
	v_pk_mul_f32 v[122:123], v[168:169], v[122:123] op_sel:[1,0] op_sel_hi:[0,1]
	v_pk_mul_f32 v[124:125], v[166:167], v[124:125] op_sel:[1,0] op_sel_hi:[0,1]
	v_pk_mul_f32 v[126:127], v[168:169], v[126:127] op_sel:[1,0] op_sel_hi:[0,1]
	v_pk_fma_f32 v[56:57], v[162:163], v[102:103], v[104:105]
	v_pk_fma_f32 v[58:59], v[164:165], v[112:113], v[106:107]
	v_pk_fma_f32 v[60:61], v[162:163], v[114:115], v[108:109]
	v_pk_fma_f32 v[62:63], v[164:165], v[116:117], v[110:111]
	v_pk_add_f32 v[28:29], v[48:49], v[50:51]
	v_pk_add_f32 v[30:31], v[52:53], v[54:55]
	v_pk_add_f32 v[2:3], v[2:3], v[24:25]
	v_pk_add_f32 v[4:5], v[4:5], v[26:27]
	v_pk_fma_f32 v[64:65], v[166:167], v[118:119], v[120:121]
	v_pk_fma_f32 v[66:67], v[168:169], v[128:129], v[122:123]
	v_pk_fma_f32 v[68:69], v[166:167], v[130:131], v[124:125]
	v_pk_fma_f32 v[70:71], v[168:169], v[132:133], v[126:127]
	v_pk_add_f32 v[32:33], v[56:57], v[58:59]
	v_pk_add_f32 v[34:35], v[60:61], v[62:63]
	v_pk_add_f32 v[2:3], v[2:3], v[28:29]
	v_pk_add_f32 v[4:5], v[4:5], v[30:31]
	s_add_i32 s1, s1, -8
	v_pk_add_f32 v[36:37], v[64:65], v[66:67]
	v_pk_add_f32 v[38:39], v[68:69], v[70:71]
	v_pk_add_f32 v[2:3], v[2:3], v[32:33]
	v_pk_add_f32 v[4:5], v[4:5], v[34:35]
	v_add_u32_e32 v6, 0x4000, v6
	v_add_u32_e32 v7, 0x80, v7
	s_cmp_eq_u32 s1, 0
	v_pk_add_f32 v[2:3], v[2:3], v[36:37]
	v_pk_add_f32 v[4:5], v[4:5], v[38:39]
	s_cbranch_scc0 .LBB0_23
; #define GAS __attribute__((address_space(1)))
; __host__ __device__ __forceinline__ size_t tl_off(int row, int k, int K) { return ((((size_t)(row >> 4) * (size_t)(K >> 5)) + (size_t)(k >> 5)) << 9) + (size_t)((row & 15) * 32 + (k & 31)); }
; __device__ __forceinline__ unsigned pk2(float lo, float hi) { return f2bf(lo) | (f2bf(hi) << 16); }
; __device__ __forceinline__ void p0_fold_staged(Frame& F) {
;     ...
;         const float ps = F.pscale[n0z + n];
;         float hi[4];
; #pragma unroll
;         for (int i = 0; i < 4; ++i) { acc[i] *= ps; hi[i] = __shfl(acc[i], (lane + 32) & 63); }
;         if (lane < 32) { u32x4 o; o.x = pk2(acc[0], acc[1]); o.y = pk2(acc[2], acc[3]); o.z = pk2(hi[0], hi[1]); o.w = pk2(hi[2], hi[3]);
;             *(GAS u32x4*)(F.Win_t + tl_off(win_drow(3 * NA + 32 * nb) + n, k0, D)) = o; }
	s_lshl_b32 s1, s0, 5
	v_or_b32_e32 v6, s1, v1
	v_mov_b32_e32 v7, 0
	v_lshl_add_u64 v[8:9], v[6:7], 2, s[50:51]
	global_load_dword v6, v[8:9], off
	v_mbcnt_lo_u32_b32 v8, -1, 0
	v_mbcnt_hi_u32_b32 v8, -1, v8
	v_and_or_b32 v8, v8, 64, v144
	v_lshlrev_b32_e32 v8, 2, v8
	v_xor_b32_e32 v11, 0x80, v8
	v_cmp_gt_u32_e32 vcc, 32, v144
	s_waitcnt vmcnt(0)
	v_pk_mul_f32 v[2:3], v[2:3], v[6:7] op_sel_hi:[1,0]
	v_pk_mul_f32 v[4:5], v[4:5], v[6:7] op_sel_hi:[1,0]
	ds_bpermute_b32 v10, v11, v3
	ds_bpermute_b32 v9, v11, v5
	ds_bpermute_b32 v8, v11, v2
	ds_bpermute_b32 v6, v11, v4
	s_and_saveexec_b64 s[4:5], vcc
	s_cbranch_execz .LBB0_26
	v_mov_b32_e32 v11, 1
	v_and_b32_sdwa v12, v3, v11 dst_sel:DWORD dst_unused:UNUSED_PAD src0_sel:WORD_1 src1_sel:DWORD
	v_and_b32_sdwa v13, v2, v11 dst_sel:DWORD dst_unused:UNUSED_PAD src0_sel:WORD_1 src1_sel:DWORD
	v_and_b32_sdwa v14, v5, v11 dst_sel:DWORD dst_unused:UNUSED_PAD src0_sel:WORD_1 src1_sel:DWORD
	v_and_b32_sdwa v11, v4, v11 dst_sel:DWORD dst_unused:UNUSED_PAD src0_sel:WORD_1 src1_sel:DWORD
	s_movk_i32 s7, 0x7fff
	v_add3_u32 v13, v2, v13, s7
	v_add3_u32 v2, v3, v12, s7
	v_add3_u32 v3, v5, v14, s7
	v_add3_u32 v4, v4, v11, s7
	v_and_b32_e32 v3, 0xffff0000, v3
	v_and_b32_e32 v4, 0xffff0000, v4
	v_or_b32_sdwa v2, v3, v2 dst_sel:DWORD dst_unused:UNUSED_PAD src0_sel:DWORD src1_sel:WORD_1
	v_or_b32_sdwa v3, v4, v13 dst_sel:DWORD dst_unused:UNUSED_PAD src0_sel:DWORD src1_sel:WORD_1
	s_waitcnt lgkmcnt(3)
	v_bfe_u32 v4, v10, 16, 1
	v_add3_u32 v4, v10, v4, s7
	s_waitcnt lgkmcnt(2)
	v_bfe_u32 v5, v9, 16, 1
	s_mov_b32 s8, 0xffff0000
	v_lshrrev_b32_e32 v4, 16, v4
	v_add3_u32 v5, v9, v5, s7
	v_and_or_b32 v4, v5, s8, v4
	s_waitcnt lgkmcnt(1)
	v_bfe_u32 v5, v8, 16, 1
	v_add3_u32 v5, v8, v5, s7
	s_waitcnt lgkmcnt(0)
	v_bfe_u32 v8, v6, 16, 1
	v_add3_u32 v6, v6, v8, s7
	s_lshl_b32 s7, s85, 7
	s_and_b32 s1, s1, 0x7fffff00
	s_and_b32 s7, s7, 0x80
	s_lshl_b32 s0, s0, 4
	s_or_b32 s1, s1, s7
	s_and_b32 s0, s0, 0x60
	s_or_b32 s0, s1, s0
	s_addk_i32 s0, 0x600
	v_lshrrev_b32_e32 v5, 16, v5
	v_or_b32_e32 v8, s0, v1
	v_and_or_b32 v5, v6, s8, v5
	v_lshrrev_b32_e32 v6, 4, v8
	v_lshlrev_b32_e32 v8, 5, v8
	s_ashr_i32 s0, s86, 3
	v_and_b32_e32 v8, 0x1e0, v8
	s_ashr_i32 s1, s0, 31
	v_and_or_b32 v10, s6, 24, v8
	v_lshlrev_b64 v[8:9], 15, v[6:7]
	v_lshl_add_u64 v[8:9], s[66:67], 0, v[8:9]
	s_lshl_b64 s[0:1], s[0:1], 10
	v_lshl_add_u64 v[8:9], v[8:9], 0, s[0:1]
	v_lshlrev_b32_e32 v6, 1, v10
	v_lshl_add_u64 v[6:7], v[8:9], 0, v[6:7]
	global_store_dwordx4 v[6:7], v[2:5], off sc1

; #define LAS __attribute__((address_space(3)))
; #define GAS __attribute__((address_space(1)))
; #define LDS_WAIT() asm volatile("s_waitcnt lgkmcnt(0)" ::: "memory")
; __device__ __forceinline__ size_t tl8_off(int row, int k, int K) { return (size_t)tl_off(row, k >> 1, K >> 1) * 2 + (k & 1); }
; __device__ __forceinline__ void p0_tile_out8(unsigned char* W8, int K, int drow0, int k0, LAS float* scr, int lane) {
;     LDS_WAIT(); asm volatile("" ::: "memory");
;     const int c = lane & 7;
; #pragma unroll
;     for (int j = 0; j < 4; ++j) { const int n = (lane >> 3) + 8 * j; const LAS float* s = scr + (8 * c) * 33 + n;
;         u32x2 o; o.x = pk4_fp8(32.f * s[0 * 33], 32.f * s[1 * 33], 32.f * s[2 * 33], 32.f * s[3 * 33]); o.y = pk4_fp8(32.f * s[4 * 33], 32.f * s[5 * 33], 32.f * s[6 * 33], 32.f * s[7 * 33]);
;         *(GAS u32x2*)(W8 + tl8_off(drow0 + n, k0 + 8 * c, K)) = o; }
;     LDS_WAIT(); asm volatile("" ::: "memory");
; __device__ __forceinline__ void p0_prologue(Frame& F) {
;     ...
;             for (int i = 0; i < 32; ++i) scr[(2 * i + (lane >> 5)) * 33 + (lane & 31)] = wv[i];
;             if (I.W8) p0_tile_out8(I.W8, I.K, I.drow0, I.ko, scr, lane); else p0_tile_out(I.WT, I.K, I.drow0, I.ko, scr, lane);
.LBB0_57:
	v_add_u32_e32 v128, 0x400, v224
	s_waitcnt vmcnt(30)
	ds_write2_b32 v224, v169, v168 offset1:66
	s_waitcnt vmcnt(28)
	ds_write2_b32 v224, v171, v170 offset0:132 offset1:198
	s_waitcnt vmcnt(26)
	ds_write2_b32 v128, v173, v172 offset0:8 offset1:74
	s_waitcnt vmcnt(24)
	ds_write2_b32 v128, v175, v174 offset0:140 offset1:206
	v_add_u32_e32 v128, 0x800, v224
	s_waitcnt vmcnt(22)
	ds_write2_b32 v128, v177, v176 offset0:16 offset1:82
	s_waitcnt vmcnt(20)
	ds_write2_b32 v128, v179, v178 offset0:148 offset1:214
	v_add_u32_e32 v128, 0xc00, v224
	s_waitcnt vmcnt(18)
	ds_write2_b32 v128, v181, v180 offset0:24 offset1:90
	s_waitcnt vmcnt(16)
	ds_write2_b32 v128, v183, v182 offset0:156 offset1:222
	v_add_u32_e32 v128, 0x1000, v224
	s_waitcnt vmcnt(14)
	ds_write2_b32 v128, v184, v185 offset0:32 offset1:98
	s_waitcnt vmcnt(12)
	ds_write2_b32 v128, v186, v187 offset0:164 offset1:230
	v_add_u32_e32 v128, 0x1400, v224
	s_waitcnt vmcnt(10)
	ds_write2_b32 v128, v188, v189 offset0:40 offset1:106
	s_waitcnt vmcnt(8)
	ds_write2_b32 v128, v190, v191 offset0:172 offset1:238
	v_add_u32_e32 v128, 0x1800, v224
	v_add_u32_e32 v136, s0, v203
	v_add_u32_e32 v134, s0, v211
	v_add_u32_e32 v132, s0, v213
	v_add_u32_e32 v130, s0, v215
	s_waitcnt vmcnt(6)
	ds_write2_b32 v128, v192, v193 offset0:48 offset1:114
	s_waitcnt vmcnt(4)
	ds_write2_b32 v128, v194, v195 offset0:180 offset1:246
	v_add_u32_e32 v128, 0x1c00, v224
	s_cmp_eq_u64 s[72:73], 0
	v_add_u32_e32 v138, s48, v205
	v_ashrrev_i32_e32 v137, 4, v136
	v_ashrrev_i32_e32 v135, 4, v134
	v_ashrrev_i32_e32 v133, 4, v132
	v_ashrrev_i32_e32 v131, 4, v130
	s_waitcnt vmcnt(2)
	ds_write2_b32 v128, v196, v197 offset0:56 offset1:122
	s_waitcnt vmcnt(0)
	ds_write2_b32 v128, v198, v199 offset0:188 offset1:254
	s_cbranch_scc1 .LBB0_77
	s_waitcnt lgkmcnt(0)
	ds_read2_b32 v[140:141], v207 offset1:8
	ds_read2_b32 v[142:143], v207 offset0:33 offset1:41
	ds_read2_b32 v[208:209], v207 offset0:66 offset1:74
	ds_read2_b32 v[218:219], v207 offset0:99 offset1:107
	ds_read2_b32 v[228:229], v207 offset0:132 offset1:140
	ds_read2_b32 v[230:231], v207 offset0:165 offset1:173
	v_mov_b32_e32 v232, v153
	s_waitcnt lgkmcnt(5)
	v_mul_f32_e32 v140, 0x42000000, v140
	s_waitcnt lgkmcnt(4)
	v_mul_f32_e32 v142, 0x42000000, v142
	ds_read2_b32 v[234:235], v207 offset0:198 offset1:206
	ds_read2_b32 v[236:237], v207 offset0:231 offset1:239
	v_cvt_pk_fp8_f32 v232, v140, v142
	s_waitcnt lgkmcnt(3)
	v_mul_f32_e32 v140, 0x42000000, v228
	s_waitcnt lgkmcnt(2)
	v_mul_f32_e32 v142, 0x42000000, v230
	v_mov_b32_e32 v233, v153
	v_cvt_pk_fp8_f32 v233, v140, v142
	s_waitcnt lgkmcnt(1)
	v_mul_f32_e32 v140, 0x42000000, v234
	s_waitcnt lgkmcnt(0)
	v_mul_f32_e32 v142, 0x42000000, v236
	v_ashrrev_i32_e32 v128, 6, v138
	v_and_b32_e32 v139, 62, v138
	v_mul_f32_e32 v152, 0x42000000, v208
	v_mul_f32_e32 v200, 0x42000000, v218
	v_cvt_pk_fp8_f32 v233, v140, v142 op_sel:[0,0,1]
	v_lshlrev_b32_e32 v140, 6, v136
	s_lshr_b32 s0, s55, 6
	v_ashrrev_i32_e32 v129, 31, v128
	v_cvt_pk_fp8_f32 v232, v152, v200 op_sel:[0,0,1]
	v_and_or_b32 v152, v140, s95, v139
	v_mul_f32_e32 v141, 0x42000000, v141
	v_mul_f32_e32 v142, 0x42000000, v143
	v_mov_b32_e32 v140, v153
	v_mad_i64_i32 v[238:239], s[8:9], s0, v137, v[128:129]
	v_cvt_pk_fp8_f32 v140, v141, v142
	v_mul_f32_e32 v142, 0x42000000, v229
	v_mul_f32_e32 v200, 0x42000000, v231
	v_mov_b32_e32 v141, v153
	v_lshlrev_b64 v[238:239], 10, v[238:239]
	v_cvt_pk_fp8_f32 v141, v142, v200
	v_lshl_add_u64 v[238:239], s[72:73], 0, v[238:239]
	v_lshl_add_u64 v[238:239], v[238:239], 0, v[152:153]
	v_mul_f32_e32 v143, 0x42000000, v209
	v_mul_f32_e32 v152, 0x42000000, v219
	v_cvt_pk_fp8_f32 v140, v143, v152 op_sel:[0,0,1]
	v_mul_f32_e32 v142, 0x42000000, v235
	v_mul_f32_e32 v143, 0x42000000, v237
	v_cvt_pk_fp8_f32 v141, v142, v143 op_sel:[0,0,1]
	v_mad_i64_i32 v[142:143], s[8:9], s0, v135, v[128:129]
	v_lshlrev_b32_e32 v152, 6, v134
	v_lshlrev_b64 v[142:143], 10, v[142:143]
	s_and_b32 s48, s48, 1
	v_and_or_b32 v152, v152, s95, v139
	v_lshl_add_u64 v[142:143], s[72:73], 0, v[142:143]
	v_lshl_add_u64 v[238:239], v[238:239], 0, s[48:49]
	v_lshl_add_u64 v[142:143], v[142:143], 0, v[152:153]
	global_store_dwordx2 v[238:239], v[232:233], off sc1
	v_lshl_add_u64 v[142:143], v[142:143], 0, s[48:49]
	ds_read2_b32 v[208:209], v207 offset0:16 offset1:24
	ds_read2_b32 v[218:219], v207 offset0:49 offset1:57
	ds_read2_b32 v[228:229], v207 offset0:82 offset1:90
	global_store_dwordx2 v[142:143], v[140:141], off sc1
	ds_read2_b32 v[140:141], v207 offset0:115 offset1:123
	ds_read2_b32 v[142:143], v207 offset0:148 offset1:156
	ds_read2_b32 v[230:231], v207 offset0:181 offset1:189
	s_waitcnt lgkmcnt(5)
	v_mul_f32_e32 v152, 0x42000000, v208
	s_waitcnt lgkmcnt(4)
	v_mul_f32_e32 v200, 0x42000000, v218
	v_mov_b32_e32 v232, v153
	ds_read2_b32 v[234:235], v207 offset0:214 offset1:222
	ds_read2_b32 v[236:237], v207 offset0:247 offset1:255
	v_cvt_pk_fp8_f32 v232, v152, v200
	s_waitcnt lgkmcnt(3)
	v_mul_f32_e32 v142, 0x42000000, v142
	s_waitcnt lgkmcnt(2)
	v_mul_f32_e32 v152, 0x42000000, v230
	v_mov_b32_e32 v233, v153
	v_cvt_pk_fp8_f32 v233, v142, v152
	v_mul_f32_e32 v202, 0x42000000, v228
	v_mul_f32_e32 v140, 0x42000000, v140
	v_cvt_pk_fp8_f32 v232, v202, v140 op_sel:[0,0,1]
	s_waitcnt lgkmcnt(1)
	v_mul_f32_e32 v140, 0x42000000, v234
	s_waitcnt lgkmcnt(0)
	v_mul_f32_e32 v142, 0x42000000, v236
	v_mad_i64_i32 v[238:239], s[8:9], s0, v133, v[128:129]
	v_cvt_pk_fp8_f32 v233, v140, v142 op_sel:[0,0,1]
	v_lshlrev_b32_e32 v140, 6, v132
	v_lshlrev_b64 v[238:239], 10, v[238:239]
	v_and_or_b32 v152, v140, s95, v139
	v_lshl_add_u64 v[238:239], s[72:73], 0, v[238:239]
	v_lshl_add_u64 v[238:239], v[238:239], 0, v[152:153]
	v_mul_f32_e32 v142, 0x42000000, v209
	v_mul_f32_e32 v152, 0x42000000, v219
	v_mov_b32_e32 v140, v153
	v_mul_f32_e32 v202, 0x42000000, v141
	v_cvt_pk_fp8_f32 v140, v142, v152
	v_mul_f32_e32 v142, 0x42000000, v143
	v_mul_f32_e32 v143, 0x42000000, v231
	v_mov_b32_e32 v141, v153
	v_cvt_pk_fp8_f32 v141, v142, v143
	v_mul_f32_e32 v200, 0x42000000, v229
	v_mul_f32_e32 v142, 0x42000000, v235
	v_mul_f32_e32 v143, 0x42000000, v237
	v_mad_i64_i32 v[128:129], s[0:1], s0, v131, v[128:129]
	v_cvt_pk_fp8_f32 v140, v200, v202 op_sel:[0,0,1]
	v_cvt_pk_fp8_f32 v141, v142, v143 op_sel:[0,0,1]
	v_lshlrev_b32_e32 v142, 6, v130
	v_lshlrev_b64 v[128:129], 10, v[128:129]
	v_and_or_b32 v152, v142, s95, v139
	v_lshl_add_u64 v[128:129], s[72:73], 0, v[128:129]
	v_lshl_add_u64 v[128:129], v[128:129], 0, v[152:153]
	v_lshl_add_u64 v[238:239], v[238:239], 0, s[48:49]
	v_lshl_add_u64 v[128:129], v[128:129], 0, s[48:49]
	global_store_dwordx2 v[238:239], v[232:233], off sc1
	global_store_dwordx2 v[128:129], v[140:141], off sc1
	s_waitcnt lgkmcnt(0)
	s_cbranch_execnz .LBB0_60
; #define LAS __attribute__((address_space(3)))
; #define GAS __attribute__((address_space(1)))
; __host__ __device__ __forceinline__ size_t tl_off(int row, int k, int K) { return ((((size_t)(row >> 4) * (size_t)(K >> 5)) + (size_t)(k >> 5)) << 9) + (size_t)((row & 15) * 32 + (k & 31)); }
; #define LDS_WAIT() asm volatile("s_waitcnt lgkmcnt(0)" ::: "memory")
; __device__ __forceinline__ unsigned pk2(float lo, float hi) { return f2bf(lo) | (f2bf(hi) << 16); }
; __device__ __forceinline__ void p0_tile_out(bf16_t* WT, int K, int drow0, int k0, LAS float* scr, int lane) {
;     LDS_WAIT(); asm volatile("" ::: "memory");
;     const int c = lane & 7;
; #pragma unroll
;     for (int j = 0; j < 4; ++j) { const int n = (lane >> 3) + 8 * j; const LAS float* s = scr + (8 * c) * 33 + n;
;         u32x4 o; o.x = pk2(s[0 * 33], s[1 * 33]); o.y = pk2(s[2 * 33], s[3 * 33]); o.z = pk2(s[4 * 33], s[5 * 33]); o.w = pk2(s[6 * 33], s[7 * 33]);
;         *(GAS u32x4*)(WT + tl_off(drow0 + n, k0 + 8 * c, K)) = o; }
;     LDS_WAIT(); asm volatile("" ::: "memory");
; }
.LBB0_59:
	s_waitcnt lgkmcnt(0)
	ds_read2_b32 v[128:129], v207 offset1:8
	ds_read2_b32 v[208:209], v207 offset0:33 offset1:41
	ds_read2_b32 v[218:219], v207 offset0:66 offset1:74
	ds_read2_b32 v[228:229], v207 offset0:99 offset1:107
	v_ashrrev_i32_e32 v142, 5, v138
	v_and_b32_e32 v200, 31, v138
	s_waitcnt lgkmcnt(3)
	v_bfe_u32 v138, v128, 16, 1
	v_add3_u32 v128, v128, v138, s96
	s_waitcnt lgkmcnt(2)
	v_bfe_u32 v138, v208, 16, 1
	ds_read2_b32 v[230:231], v207 offset0:132 offset1:140
	v_lshrrev_b32_e32 v128, 16, v128
	v_add3_u32 v138, v208, v138, s96
	ds_read2_b32 v[232:233], v207 offset0:165 offset1:173
	v_and_or_b32 v138, v138, s97, v128
	s_waitcnt lgkmcnt(3)
	v_bfe_u32 v128, v218, 16, 1
	v_add3_u32 v128, v218, v128, s96
	s_waitcnt lgkmcnt(2)
	v_bfe_u32 v139, v228, 16, 1
	ds_read2_b32 v[234:235], v207 offset0:198 offset1:206
	v_lshrrev_b32_e32 v128, 16, v128
	v_add3_u32 v139, v228, v139, s96
	ds_read2_b32 v[236:237], v207 offset0:231 offset1:239
	v_and_or_b32 v139, v139, s97, v128
	s_waitcnt lgkmcnt(3)
	v_bfe_u32 v128, v230, 16, 1
	v_add3_u32 v128, v230, v128, s96
	s_waitcnt lgkmcnt(2)
	v_bfe_u32 v140, v232, 16, 1
	v_lshrrev_b32_e32 v128, 16, v128
	v_add3_u32 v140, v232, v140, s96
	v_and_or_b32 v140, v140, s97, v128
	s_waitcnt lgkmcnt(1)
	v_bfe_u32 v128, v234, 16, 1
	v_add3_u32 v128, v234, v128, s96
	s_waitcnt lgkmcnt(0)
	v_bfe_u32 v141, v236, 16, 1
	v_lshrrev_b32_e32 v128, 16, v128
	v_add3_u32 v141, v236, v141, s96
	s_lshr_b32 s8, s55, 5
	v_ashrrev_i32_e32 v143, 31, v142
	v_and_or_b32 v141, v141, s97, v128
	v_lshlrev_b32_e32 v128, 5, v136
	v_mad_i64_i32 v[238:239], s[0:1], s8, v137, v[142:143]
	v_and_or_b32 v128, v128, s54, v200
	v_lshlrev_b64 v[136:137], 10, v[238:239]
	v_lshlrev_b32_e32 v152, 1, v128
	v_bfe_u32 v128, v129, 16, 1
	v_lshl_add_u64 v[136:137], s[68:69], 0, v[136:137]
	v_add3_u32 v128, v129, v128, s96
	v_bfe_u32 v129, v209, 16, 1
	v_lshl_add_u64 v[136:137], v[136:137], 0, v[152:153]
	v_lshrrev_b32_e32 v128, 16, v128
	v_add3_u32 v129, v209, v129, s96
	global_store_dwordx4 v[136:137], v[138:141], off sc1
	v_and_or_b32 v136, v129, s97, v128
	v_bfe_u32 v128, v219, 16, 1
	v_add3_u32 v128, v219, v128, s96
	v_bfe_u32 v129, v229, 16, 1
	v_lshrrev_b32_e32 v128, 16, v128
	v_add3_u32 v129, v229, v129, s96
	v_and_or_b32 v137, v129, s97, v128
	v_bfe_u32 v128, v231, 16, 1
	v_add3_u32 v128, v231, v128, s96
	v_bfe_u32 v129, v233, 16, 1
	v_lshrrev_b32_e32 v128, 16, v128
	v_add3_u32 v129, v233, v129, s96
	v_and_or_b32 v138, v129, s97, v128
	v_bfe_u32 v128, v235, 16, 1
	v_add3_u32 v128, v235, v128, s96
	v_bfe_u32 v129, v237, 16, 1
	v_lshrrev_b32_e32 v128, 16, v128
	v_add3_u32 v129, v237, v129, s96
	v_and_or_b32 v139, v129, s97, v128
	v_mad_i64_i32 v[128:129], s[0:1], s8, v135, v[142:143]
	v_lshlrev_b32_e32 v134, 5, v134
	v_and_or_b32 v134, v134, s54, v200
	v_lshlrev_b64 v[128:129], 10, v[128:129]
	v_lshl_add_u64 v[128:129], s[68:69], 0, v[128:129]
	v_lshlrev_b32_e32 v152, 1, v134
	ds_read2_b32 v[140:141], v207 offset0:16 offset1:24
	v_lshl_add_u64 v[128:129], v[128:129], 0, v[152:153]
	global_store_dwordx4 v[128:129], v[136:139], off sc1
	ds_read2_b32 v[128:129], v207 offset0:49 offset1:57
	ds_read2_b32 v[138:139], v207 offset0:82 offset1:90
	ds_read2_b32 v[208:209], v207 offset0:115 offset1:123
	s_waitcnt lgkmcnt(3)
	v_bfe_u32 v134, v140, 16, 1
	v_add3_u32 v134, v140, v134, s96
	s_waitcnt lgkmcnt(2)
	v_bfe_u32 v135, v128, 16, 1
	ds_read2_b32 v[218:219], v207 offset0:148 offset1:156
	v_lshrrev_b32_e32 v134, 16, v134
	v_add3_u32 v128, v128, v135, s96
	ds_read2_b32 v[228:229], v207 offset0:181 offset1:189
	v_and_or_b32 v134, v128, s97, v134
	s_waitcnt lgkmcnt(3)
	v_bfe_u32 v128, v138, 16, 1
	v_add3_u32 v128, v138, v128, s96
	s_waitcnt lgkmcnt(2)
	v_bfe_u32 v135, v208, 16, 1
	ds_read2_b32 v[230:231], v207 offset0:214 offset1:222
	v_lshrrev_b32_e32 v128, 16, v128
	v_add3_u32 v135, v208, v135, s96
	ds_read2_b32 v[232:233], v207 offset0:247 offset1:255
	v_and_or_b32 v135, v135, s97, v128
	s_waitcnt lgkmcnt(3)
	v_bfe_u32 v128, v218, 16, 1
	v_add3_u32 v128, v218, v128, s96
	s_waitcnt lgkmcnt(2)
	v_bfe_u32 v136, v228, 16, 1
	v_lshrrev_b32_e32 v128, 16, v128
	v_add3_u32 v136, v228, v136, s96
	v_and_or_b32 v136, v136, s97, v128
	s_waitcnt lgkmcnt(1)
	v_bfe_u32 v128, v230, 16, 1
	v_add3_u32 v128, v230, v128, s96
	s_waitcnt lgkmcnt(0)
	v_bfe_u32 v137, v232, 16, 1
	v_lshrrev_b32_e32 v128, 16, v128
	v_add3_u32 v137, v232, v137, s96
	v_and_or_b32 v137, v137, s97, v128
	v_mad_i64_i32 v[234:235], s[0:1], s8, v133, v[142:143]
	v_lshlrev_b32_e32 v128, 5, v132
	v_and_or_b32 v128, v128, s54, v200
	v_lshlrev_b64 v[132:133], 10, v[234:235]
	v_lshl_add_u64 v[132:133], s[68:69], 0, v[132:133]
	v_lshlrev_b32_e32 v152, 1, v128
	v_lshl_add_u64 v[132:133], v[132:133], 0, v[152:153]
	v_bfe_u32 v128, v141, 16, 1
	global_store_dwordx4 v[132:133], v[134:137], off sc1
	v_add3_u32 v128, v141, v128, s96
	v_bfe_u32 v132, v129, 16, 1
	v_lshrrev_b32_e32 v128, 16, v128
	v_add3_u32 v129, v129, v132, s96
	v_and_or_b32 v132, v129, s97, v128
	v_bfe_u32 v128, v139, 16, 1
	v_add3_u32 v128, v139, v128, s96
	v_bfe_u32 v129, v209, 16, 1
	v_lshrrev_b32_e32 v128, 16, v128
	v_add3_u32 v129, v209, v129, s96
	v_and_or_b32 v133, v129, s97, v128
	v_bfe_u32 v128, v219, 16, 1
	v_add3_u32 v128, v219, v128, s96
	v_bfe_u32 v129, v229, 16, 1
	v_lshrrev_b32_e32 v128, 16, v128
	v_add3_u32 v129, v229, v129, s96
	v_and_or_b32 v134, v129, s97, v128
	v_bfe_u32 v128, v231, 16, 1
	v_add3_u32 v128, v231, v128, s96
	v_bfe_u32 v129, v233, 16, 1
	v_lshrrev_b32_e32 v128, 16, v128
	v_add3_u32 v129, v233, v129, s96
	v_and_or_b32 v135, v129, s97, v128
	v_mad_i64_i32 v[128:129], s[0:1], s8, v131, v[142:143]
	v_lshlrev_b32_e32 v130, 5, v130
	v_and_or_b32 v130, v130, s54, v200
	v_lshlrev_b64 v[128:129], 10, v[128:129]
	v_lshl_add_u64 v[128:129], s[68:69], 0, v[128:129]
	v_lshlrev_b32_e32 v152, 1, v130
	v_lshl_add_u64 v[128:129], v[128:129], 0, v[152:153]
	global_store_dwordx4 v[128:129], v[132:135], off sc1
	s_waitcnt lgkmcnt(0)
